# speedup vs baseline: 1.0010x; 1.0010x over previous
; __device__ __forceinline__ int ptid() { int t = __builtin_amdgcn_workitem_id_x(); asm volatile("" : "+v"(t)); return t; }
; __device__ __forceinline__ float bflo(unsigned u) { return __uint_as_float(u << 16); }
; __device__ __forceinline__ float bfhi(unsigned u) { return __uint_as_float(u & 0xffff0000u); }
; static __device__ __forceinline__ void attn_item(const Params& p, int head, int j, char* smraw) {
;   int tseq0, S, qb;
;   if (j < 512) { const int seq = j >> 6; qb = j & 63; S = 8192; tseq0 = TPR + seq * 8192; }
;   else { const int jj = j - 512; const int seq = jj >> 4; qb = jj & 15; S = 2048; tseq0 = seq * 2048; }
;   const u16* Qb = (const u16*)(p.ws + WS_QB); const u16* Kb = (const u16*)(p.ws + WS_KB); const u16* Vt = (const u16*)(p.ws + WS_VT);
;   u16* Ao = (u16*)(p.ws + WS_ATT);
;   const int tid = ptid(), lane = tid & 63, w = tid >> 6, l15 = lane & 15, quad = lane >> 4;
;   u16* sK[2]; u16* sV[2];
;   sK[0] = (u16*)smraw; sV[0] = sK[0] + 64 * 128; sK[1] = sV[0] + 64 * 64; sV[1] = sK[1] + 64 * 128;
;   const int qrow0 = tseq0 + qb * 128 + w * 32;
;   bf16x8 qf[2][3];
; #pragma unroll
;   for (int qt = 0; qt < 2; ++qt)
; #pragma unroll
;     for (int ks = 0; ks < 3; ++ks)
;     {
;       const u32x4 qraw = *(const u32x4*)(Qb + (size_t)(qrow0 + qt * 16 + l15) * 768 + head * 96 + ks * 32 + quad * 8);
;       constexpr float CQ = 0.10206207261596577f * 1.4426950408889634f;
;       u32x4 qs;
; #pragma unroll
;       for (int e = 0; e < 4; ++e) qs[e] = cvtpk(bflo(qraw[e]) * CQ, bfhi(qraw[e]) * CQ);
;       qf[qt][ks] = *(bf16x8*)&qs;
;     }
;   int krow[3], kcol[3], klds[3];
; #pragma unroll
;   for (int i = 0; i < 3; ++i) {
;     const int c = tid + 256 * i, kv = c / 12, kc = c % 12;
;     const int rho = (kv & 32) | (((kv >> 2) & 1) << 4) | (((kv >> 3) & 3) << 2) | (kv & 3);
;     krow[i] = kv; kcol[i] = kc * 8; klds[i] = rho * 128 + ((kc ^ (rho & 15)) << 3);
;   }
.LBB0_373:
	s_or_b64 exec, exec, s[0:1]
	s_waitcnt lgkmcnt(0)
	s_barrier
	ds_read_b32 v0, v176
	s_mov_b64 s[0:1], -1
	s_waitcnt lgkmcnt(0)
	s_barrier
	v_cmp_lt_i32_e32 vcc, s22, v0
	v_readfirstlane_b32 s3, v0
	s_cbranch_vccnz .LBB0_368
	s_lshl_b32 s0, s3, 7
	s_cmpk_lt_i32 s3, 0x200
	s_cselect_b32 s1, 63, 15
	s_cselect_b32 s12, s23, 0x7ffff800
	s_cselect_b32 s13, s24, 0xffff0000
	s_cselect_b32 s2, 0x80, 32
	s_and_b32 s1, s1, s3
	s_and_b32 s0, s12, s0
	s_add_i32 s0, s0, s13
	s_waitcnt vmcnt(24)
	v_mov_b32_e32 v70, v174
	s_lshl_b32 s1, s1, 7
	s_add_i32 s1, s0, s1
	s_waitcnt vmcnt(23)
	v_and_b32_e32 v71, 15, v70
	v_ashrrev_i32_e32 v0, 1, v70
	v_bfe_u32 v178, v70, 4, 2
	v_and_b32_e32 v0, 0xffffffe0, v0
	v_or_b32_e32 v1, s1, v71
	v_add_u32_e32 v130, v1, v0
	v_lshlrev_b32_e32 v128, 4, v178
	v_lshl_add_u64 v[12:13], s[46:47], 0, v[128:129]
	v_or_b32_e32 v132, 16, v130
	v_mad_i64_i32 v[8:9], s[12:13], v130, s25, v[12:13]
	v_mad_i64_i32 v[20:21], s[12:13], v132, s25, v[12:13]
	global_load_dwordx4 v[0:3], v[8:9], off
	global_load_dwordx4 v[4:7], v[8:9], off offset:64
	s_nop 0
	global_load_dwordx4 v[8:11], v[8:9], off offset:128
	s_nop 0
	global_load_dwordx4 v[12:15], v[20:21], off
	global_load_dwordx4 v[16:19], v[20:21], off offset:64
	s_ashr_i32 s1, s0, 31
	global_load_dwordx4 v[20:23], v[20:21], off offset:128
	s_mul_i32 s12, s0, 0x600
	s_mul_hi_i32 s3, s0, 0x600
	s_add_u32 s12, s64, s12
	s_addc_u32 s13, s65, s3
	s_lshl_b64 s[50:51], s[0:1], 1
	v_ashrrev_i32_e32 v77, 3, v70
	s_waitcnt vmcnt(28)
	v_lshrrev_b32_e32 v72, 4, v70
	v_ashrrev_i32_e32 v131, 31, v130
	v_ashrrev_i32_e32 v133, 31, v132
	s_mov_b32 s3, 3
	v_mov_b32_e32 v189, 0
	v_mov_b32_e32 v190, 0
	s_waitcnt vmcnt(5)
	v_lshlrev_b32_e32 v24, 16, v0
	v_and_b32_e32 v25, 0xffff0000, v0
	v_lshlrev_b32_e32 v0, 16, v1
	v_and_b32_e32 v1, 0xffff0000, v1
	v_lshlrev_b32_e32 v26, 16, v2
	v_and_b32_e32 v27, 0xffff0000, v2
	v_pk_mul_f32 v[24:25], v[24:25], s[6:7] op_sel_hi:[1,0]
	s_waitcnt vmcnt(2)
	v_lshlrev_b32_e32 v48, 16, v12
	v_and_b32_e32 v49, 0xffff0000, v12
	v_lshlrev_b32_e32 v2, 16, v3
	v_and_b32_e32 v3, 0xffff0000, v3
	v_pk_mul_f32 v[36:37], v[0:1], s[6:7] op_sel_hi:[1,0]
	v_pk_mul_f32 v[26:27], v[26:27], s[6:7] op_sel_hi:[1,0]
	v_lshlrev_b32_e32 v12, 16, v13
	v_and_b32_e32 v13, 0xffff0000, v13
	v_lshlrev_b32_e32 v50, 16, v14
	v_and_b32_e32 v51, 0xffff0000, v14
	v_cvt_pk_bf16_f32 v0, v24, v25
	v_pk_mul_f32 v[24:25], v[48:49], s[6:7] op_sel_hi:[1,0]
	v_pk_mul_f32 v[38:39], v[2:3], s[6:7] op_sel_hi:[1,0]
	v_cvt_pk_bf16_f32 v2, v26, v27
	v_pk_mul_f32 v[26:27], v[12:13], s[6:7] op_sel_hi:[1,0]
	v_cvt_pk_bf16_f32 v12, v24, v25
	v_pk_mul_f32 v[24:25], v[50:51], s[6:7] op_sel_hi:[1,0]
	v_lshlrev_b32_e32 v28, 16, v4
	v_cvt_pk_bf16_f32 v14, v24, v25
	v_lshlrev_b32_e32 v24, 16, v15
	v_and_b32_e32 v25, 0xffff0000, v15
	v_pk_mul_f32 v[24:25], v[24:25], s[6:7] op_sel_hi:[1,0]
	v_and_b32_e32 v29, 0xffff0000, v4
	v_cvt_pk_bf16_f32 v15, v24, v25
	s_waitcnt vmcnt(1)
	v_lshlrev_b32_e32 v24, 16, v16
	v_and_b32_e32 v25, 0xffff0000, v16
	v_pk_mul_f32 v[24:25], v[24:25], s[6:7] op_sel_hi:[1,0]
	v_lshlrev_b32_e32 v4, 16, v5
	v_cvt_pk_bf16_f32 v16, v24, v25
	v_lshlrev_b32_e32 v24, 16, v17
	v_and_b32_e32 v25, 0xffff0000, v17
	v_pk_mul_f32 v[24:25], v[24:25], s[6:7] op_sel_hi:[1,0]
	v_and_b32_e32 v5, 0xffff0000, v5
	v_cvt_pk_bf16_f32 v17, v24, v25
	v_lshlrev_b32_e32 v24, 16, v18
	v_and_b32_e32 v25, 0xffff0000, v18
	v_pk_mul_f32 v[24:25], v[24:25], s[6:7] op_sel_hi:[1,0]
	v_pk_mul_f32 v[40:41], v[4:5], s[6:7] op_sel_hi:[1,0]
	v_cvt_pk_bf16_f32 v18, v24, v25
	v_lshlrev_b32_e32 v24, 16, v19
	v_and_b32_e32 v25, 0xffff0000, v19
	v_pk_mul_f32 v[24:25], v[24:25], s[6:7] op_sel_hi:[1,0]
	v_cvt_pk_bf16_f32 v5, v40, v41
	v_cvt_pk_bf16_f32 v19, v24, v25
	s_waitcnt vmcnt(0)
	v_lshlrev_b32_e32 v24, 16, v20
	v_and_b32_e32 v25, 0xffff0000, v20
	v_pk_mul_f32 v[24:25], v[24:25], s[6:7] op_sel_hi:[1,0]
	v_lshlrev_b32_e32 v40, 16, v21
	v_and_b32_e32 v41, 0xffff0000, v21
	v_mul_hi_i32 v21, v70, s26
	v_cvt_pk_bf16_f32 v20, v24, v25
	v_lshrrev_b32_e32 v24, 31, v21
	v_ashrrev_i32_e32 v21, 1, v21
	v_lshlrev_b32_e32 v34, 16, v10
	v_and_b32_e32 v35, 0xffff0000, v10
	v_lshlrev_b32_e32 v10, 16, v11
	v_and_b32_e32 v11, 0xffff0000, v11
	v_add_u32_e32 v74, v21, v24
	v_pk_mul_f32 v[46:47], v[10:11], s[6:7] op_sel_hi:[1,0]
	v_mul_lo_u32 v21, v74, 12
	v_cvt_pk_bf16_f32 v11, v46, v47
	v_sub_u32_e32 v46, v70, v21
	v_add_u32_e32 v21, 0x100, v70
	v_mul_hi_i32 v25, v21, s26
	v_lshlrev_b32_e32 v32, 16, v8
	v_and_b32_e32 v33, 0xffff0000, v8
	v_lshlrev_b32_e32 v8, 16, v9
	v_and_b32_e32 v9, 0xffff0000, v9
	v_cvt_pk_bf16_f32 v13, v26, v27
	v_lshrrev_b32_e32 v26, 31, v25
	v_ashrrev_i32_e32 v25, 1, v25
	v_pk_mul_f32 v[44:45], v[8:9], s[6:7] op_sel_hi:[1,0]
	v_add_u32_e32 v75, v25, v26
	v_cvt_pk_bf16_f32 v9, v44, v45
	v_mul_lo_u32 v25, v75, 12
	v_pk_mul_f32 v[44:45], v[40:41], s[6:7] op_sel_hi:[1,0]
	v_sub_u32_e32 v47, v21, v25
	v_ashrrev_i32_e32 v78, 3, v21
	v_cvt_pk_bf16_f32 v21, v44, v45
	v_lshlrev_b32_e32 v44, 16, v22
	v_and_b32_e32 v45, 0xffff0000, v22
	v_pk_mul_f32 v[44:45], v[44:45], s[6:7] op_sel_hi:[1,0]
	v_add_u32_e32 v25, 0x200, v70
	v_cvt_pk_bf16_f32 v22, v44, v45
	v_lshlrev_b32_e32 v44, 16, v23
	v_and_b32_e32 v45, 0xffff0000, v23
	v_pk_mul_f32 v[44:45], v[44:45], s[6:7] op_sel_hi:[1,0]
	v_pk_mul_f32 v[28:29], v[28:29], s[6:7] op_sel_hi:[1,0]
	v_cvt_pk_bf16_f32 v23, v44, v45
	v_lshlrev_b32_e32 v44, 2, v74
	v_lshrrev_b32_e32 v45, 1, v74
	v_mul_hi_i32 v27, v25, s26
	v_and_b32_e32 v44, 16, v44
	v_and_b32_e32 v45, 12, v45
	v_and_b32_e32 v51, 35, v74
	v_cvt_pk_bf16_f32 v4, v28, v29
	v_lshrrev_b32_e32 v28, 31, v27
	v_ashrrev_i32_e32 v27, 1, v27
; static __device__ __forceinline__ void attn_item(const Params& p, int head, int j, char* smraw) {
;     ...
;   int krow[3], kcol[3], klds[3];
; #pragma unroll
;   for (int i = 0; i < 3; ++i) {
;     const int c = tid + 256 * i, kv = c / 12, kc = c % 12;
;     const int rho = (kv & 32) | (((kv >> 2) & 1) << 4) | (((kv >> 3) & 3) << 2) | (kv & 3);
;     krow[i] = kv; kcol[i] = kc * 8; klds[i] = rho * 128 + ((kc ^ (rho & 15)) << 3);
;   }
;   const u16* Kg = Kb + (size_t)tseq0 * 768 + head * 96;
;   const u16* Vg = Vt + (size_t)(head * 64) * T + tseq0;
;   u32x4 rkA[3], rvA[2], rkB[3], rvB[2];
;     ...
;   f32x4 oacc[4][2];
; #pragma unroll
;   for (int a = 0; a < 4; ++a)
; #pragma unroll
;     for (int b = 0; b < 2; ++b) oacc[a][b] = f32x4{0.f, 0.f, 0.f, 0.f};
;     ...
;   ATT_LOAD(rkA, rvA, 0); ATT_LOAD(rkB, rvB, 1);
;   ATT_STORE(rkA, rvA, 0);
;   __syncthreads();
	v_and_b32_e32 v50, 3, v74
	v_or3_b32 v44, v51, v44, v45
	v_add_u32_e32 v76, v27, v28
	v_lshlrev_b32_e32 v79, 7, v44
	v_bitop3_b32 v44, v45, v46, v50 bitop3:0x36
	v_lshlrev_b32_e32 v24, 3, v46
	v_mul_lo_u32 v27, v76, 12
	v_lshlrev_b32_e32 v80, 3, v44
	v_lshlrev_b32_e32 v44, 2, v75
	v_lshrrev_b32_e32 v45, 1, v75
	v_sub_u32_e32 v73, v25, v27
	v_mov_b64_e32 v[48:49], s[12:13]
	v_ashrrev_i32_e32 v25, 31, v24
	v_and_b32_e32 v44, 16, v44
	v_and_b32_e32 v45, 12, v45
	v_and_b32_e32 v50, 35, v75
	v_pk_mul_f32 v[34:35], v[34:35], s[6:7] op_sel_hi:[1,0]
	v_mad_i64_i32 v[28:29], s[12:13], v74, s25, v[48:49]
	v_lshlrev_b64 v[64:65], 1, v[24:25]
	v_and_b32_e32 v46, 3, v75
	v_or3_b32 v44, v50, v44, v45
	v_cvt_pk_bf16_f32 v10, v34, v35
	v_lshl_add_u64 v[24:25], v[28:29], 0, v[64:65]
	v_mad_i64_i32 v[28:29], s[12:13], v75, s25, v[48:49]
	v_mad_i64_i32 v[34:35], s[12:13], v76, s25, v[48:49]
	v_lshlrev_b32_e32 v81, 7, v44
	v_bitop3_b32 v44, v45, v47, v46 bitop3:0x36
	v_pk_mul_f32 v[32:33], v[32:33], s[6:7] op_sel_hi:[1,0]
	s_add_u32 s12, s66, s50
	v_lshlrev_b32_e32 v82, 3, v44
	v_lshlrev_b32_e32 v44, 2, v76
	v_lshlrev_b32_e32 v30, 16, v6
	v_and_b32_e32 v31, 0xffff0000, v6
	v_lshlrev_b32_e32 v6, 16, v7
	v_and_b32_e32 v7, 0xffff0000, v7
	v_cvt_pk_bf16_f32 v1, v36, v37
	v_cvt_pk_bf16_f32 v8, v32, v33
	v_lshlrev_b32_e32 v26, 3, v47
	v_lshlrev_b32_e32 v32, 3, v73
	s_addc_u32 s13, s67, s51
	v_lshlrev_b32_e32 v36, 4, v70
	v_and_b32_e32 v83, 16, v44
	v_lshrrev_b32_e32 v44, 1, v76
	v_pk_mul_f32 v[42:43], v[6:7], s[6:7] op_sel_hi:[1,0]
	v_ashrrev_i32_e32 v27, 31, v26
	v_ashrrev_i32_e32 v33, 31, v32
	v_and_b32_e32 v128, 0x70, v36
	v_and_b32_e32 v84, 12, v44
	v_add_u32_e32 v44, 64, v74
	v_add_u32_e32 v50, 64, v75
	v_add_u32_e32 v52, 64, v76
	v_mov_b64_e32 v[56:57], s[12:13]
	v_cvt_pk_bf16_f32 v7, v42, v43
	v_lshlrev_b64 v[66:67], 1, v[26:27]
	v_lshlrev_b64 v[68:69], 1, v[32:33]
	v_lshl_add_u64 v[42:43], s[12:13], 0, v[128:129]
	v_mad_i64_i32 v[44:45], s[68:69], v44, s25, v[48:49]
	v_mad_i64_i32 v[50:51], s[68:69], v50, s25, v[48:49]
	v_mad_i64_i32 v[48:49], s[68:69], v52, s25, v[48:49]
	v_mad_i64_i32 v[58:59], s[12:13], v77, s27, v[56:57]
	v_mad_i64_i32 v[56:57], s[12:13], v78, s27, v[56:57]
	v_pk_mul_f32 v[30:31], v[30:31], s[6:7] op_sel_hi:[1,0]
	v_lshl_add_u64 v[28:29], v[28:29], 0, v[66:67]
	v_lshl_add_u64 v[32:33], v[34:35], 0, v[68:69]
	v_mad_i64_i32 v[36:37], s[68:69], v77, s27, v[42:43]
	v_mad_i64_i32 v[40:41], s[68:69], v78, s27, v[42:43]
	v_lshl_add_u64 v[44:45], v[44:45], 0, v[64:65]
	v_lshl_add_u64 v[50:51], v[50:51], 0, v[66:67]
	v_lshl_add_u64 v[52:53], v[48:49], 0, v[68:69]
	v_lshl_add_u64 v[58:59], v[58:59], 0, v[128:129]
	v_lshl_add_u64 v[60:61], v[56:57], 0, v[128:129]
	v_cvt_pk_bf16_f32 v3, v38, v39
	v_cvt_pk_bf16_f32 v6, v30, v31
	global_load_dwordx4 v[24:27], v[24:25], off
	s_nop 0
	global_load_dwordx4 v[28:31], v[28:29], off
	v_and_b32_e32 v85, 3, v76
	global_load_dwordx4 v[32:35], v[32:33], off
	v_and_b32_e32 v86, 35, v76
	global_load_dwordx4 v[36:39], v[36:37], off
	v_or3_b32 v83, v86, v83, v84
	global_load_dwordx4 v[40:43], v[40:41], off
	v_bitop3_b32 v73, v84, v73, v85 bitop3:0x36
	global_load_dwordx4 v[44:47], v[44:45], off
	s_nop 0
	global_load_dwordx4 v[48:51], v[50:51], off
	s_nop 0
	global_load_dwordx4 v[52:55], v[52:53], off
	s_nop 0
	global_load_dwordx4 v[56:59], v[58:59], off offset:128
	s_nop 0
	global_load_dwordx4 v[60:63], v[60:61], off offset:128
	v_lshlrev_b32_e32 v83, 7, v83
	v_lshlrev_b32_e32 v73, 3, v73
	v_add_lshl_u32 v181, v83, v73, 1
	v_xor_b32_e32 v73, v77, v70
	v_lshlrev_b32_e32 v73, 4, v73
	v_and_b32_e32 v73, 0x70, v73
	v_add_lshl_u32 v179, v79, v80, 1
	v_lshl_or_b32 v182, v77, 7, v73
	v_xor_b32_e32 v73, v78, v70
	v_bitop3_b32 v79, v72, v71, 3 bitop3:0x6c
	v_lshlrev_b32_e32 v80, 8, v71
	v_lshlrev_b32_e32 v73, 4, v73
	v_lshl_or_b32 v184, v79, 4, v80
	v_bitop3_b32 v79, v178, v71, 4 bitop3:0x36
	v_and_b32_e32 v73, 0x70, v73
	v_lshl_or_b32 v185, v79, 4, v80
	v_and_b32_e32 v79, 7, v70
	v_lshl_or_b32 v183, v78, 7, v73
	v_lshlrev_b32_e32 v73, 7, v71
	v_bitop3_b32 v70, v72, v79, 3 bitop3:0x6c
	v_bitop3_b32 v71, v178, v71, 8 bitop3:0x36
	v_lshl_or_b32 v187, v70, 4, v73
	v_bitop3_b32 v70, v178, v79, 4 bitop3:0x36
	v_lshl_or_b32 v186, v71, 4, v80
	v_lshl_or_b32 v188, v70, 4, v73
	v_mov_b64_e32 v[70:71], s[4:5]
	v_mad_i64_i32 v[72:73], s[12:13], v77, s27, v[70:71]
	v_lshlrev_b32_e32 v128, 4, v79
	v_mad_i64_i32 v[70:71], s[12:13], v78, s27, v[70:71]
	v_lshl_add_u64 v[70:71], v[70:71], 0, v[128:129]
	v_lshl_add_u64 v[72:73], v[72:73], 0, v[128:129]
	v_lshl_add_u64 v[136:137], v[70:71], 0, s[50:51]
	v_mov_b64_e32 v[70:71], s[34:35]
	v_lshl_add_u64 v[134:135], v[72:73], 0, s[50:51]
	v_mad_i64_i32 v[72:73], s[12:13], v76, s25, v[70:71]
	v_mad_i64_i32 v[72:73], s[12:13], s0, v177, v[72:73]
	v_lshl_add_u64 v[138:139], v[72:73], 0, v[68:69]
	v_mad_i64_i32 v[68:69], s[12:13], v75, s25, v[70:71]
	v_mad_i64_i32 v[68:69], s[12:13], s0, v177, v[68:69]
	v_lshl_add_u64 v[140:141], v[68:69], 0, v[66:67]
	v_mad_i64_i32 v[66:67], s[12:13], v74, s25, v[70:71]
	v_mad_i64_i32 v[66:67], s[0:1], s0, v177, v[66:67]
	v_lshl_add_u64 v[142:143], v[66:67], 0, v[64:65]
	s_add_u32 s98, s60, 0x27030000
	s_addc_u32 s99, s61, 0
	v_lshl_add_u64 v[138:139], v[138:139], 0, s[98:99]
	v_lshl_add_u64 v[140:141], v[140:141], 0, s[98:99]
	v_lshl_add_u64 v[142:143], v[142:143], 0, s[98:99]
	s_add_u32 s98, s60, 0x30000000
	s_addc_u32 s99, s61, 0
	v_lshl_add_u64 v[134:135], v[134:135], 0, s[98:99]
	v_lshl_add_u64 v[136:137], v[136:137], 0, s[98:99]
	s_mov_b32 s98, 0x18000
	s_mov_b32 s99, 0
	v_mov_b32_e32 v66, v129
	v_mov_b32_e32 v67, v129
	v_add_lshl_u32 v180, v81, v82, 1
	v_mov_b32_e32 v128, v129
	v_mov_b32_e32 v64, v129
	v_mov_b32_e32 v65, v129
	v_mov_b64_e32 v[82:83], v[66:67]
	v_mov_b64_e32 v[70:71], v[66:67]
	v_mov_b64_e32 v[86:87], v[66:67]
	v_mov_b64_e32 v[74:75], v[66:67]
	v_mov_b64_e32 v[90:91], v[66:67]
	v_mov_b64_e32 v[78:79], v[66:67]
	v_mov_b64_e32 v[94:95], v[66:67]
	v_mov_b64_e32 v[80:81], v[64:65]
	v_mov_b64_e32 v[68:69], v[64:65]
	v_mov_b64_e32 v[84:85], v[64:65]
	v_mov_b64_e32 v[72:73], v[64:65]
	v_mov_b64_e32 v[88:89], v[64:65]
	v_mov_b64_e32 v[76:77], v[64:65]
	v_mov_b64_e32 v[92:93], v[64:65]
	v_mov_b64_e32 v[144:145], v[128:129]
	s_waitcnt vmcnt(9)
	ds_write_b128 v179, v[24:27]
	s_waitcnt vmcnt(8)
	ds_write_b128 v180, v[28:31]
	s_waitcnt vmcnt(7)
	ds_write_b128 v181, v[32:35]
	s_waitcnt vmcnt(6)
	ds_write_b128 v182, v[36:39] offset:16384
	s_waitcnt vmcnt(5)
	ds_write_b128 v183, v[40:43] offset:16384
	s_waitcnt lgkmcnt(0)
	s_barrier
	s_branch .LBB0_376

; static __device__ __forceinline__ void attn_item(const Params& p, int head, int j, char* smraw) {
;     ...
;   for (int t = 0; t < NT; t += 2) {
;     if (t + 2 < NT) ATT_LOAD(rkA, rvA, t + 2);
.LBB0_376:
	s_add_i32 s12, s3, -1
	s_cmp_lt_u32 s12, s2
	s_cselect_b64 s[50:51], -1, 0
	s_cmp_ge_u32 s12, s2
	s_cbranch_scc1 .LBB0_378
	global_load_dwordx4 v[24:27], v[142:143], off
	global_load_dwordx4 v[28:31], v[140:141], off
	global_load_dwordx4 v[32:35], v[138:139], off
	global_load_dwordx4 v[36:39], v[134:135], off offset:256
	global_load_dwordx4 v[40:43], v[136:137], off offset:256

; #define MFMA16(a, b, c) __builtin_amdgcn_mfma_f32_16x16x32_bf16((a), (b), (c), 0, 0, 0)
; static __device__ __forceinline__ void attn_item(const Params& p, int head, int j, char* smraw) {
;     ...
;     bf16x8 pf[2][2];
; #pragma unroll
;     for (int qt = 0; qt < 2; ++qt) {
;       float ps = 0.f;
; #pragma unroll
;       for (int kt = 0; kt < 4; ++kt)
; #pragma unroll
;         for (int r = 0; r < 4; ++r) {
;           const float pv = __builtin_amdgcn_exp2f(sacc[kt][qt][r]);
;           sacc[kt][qt][r] = pv; ps += pv;
;         }
;       lrun[qt] += ps;
; #pragma unroll
;       for (int k2 = 0; k2 < 2; ++k2) {
;         u32x4 pk = {cvtpk(sacc[2 * k2][qt][0], sacc[2 * k2][qt][1]), cvtpk(sacc[2 * k2][qt][2], sacc[2 * k2][qt][3]),
;                     cvtpk(sacc[2 * k2 + 1][qt][0], sacc[2 * k2 + 1][qt][1]), cvtpk(sacc[2 * k2 + 1][qt][2], sacc[2 * k2 + 1][qt][3])};
;         pf[qt][k2] = *(bf16x8*)&pk;
;       }
;     }
;     {
;       bf16x8 vf[2][4];
; #pragma unroll
;       for (int k2 = 0; k2 < 2; ++k2)
; #pragma unroll
;         for (int dt = 0; dt < 4; ++dt) vf[k2][dt] = *(const bf16x8*)(cV + (dt * 16 + l15) * 64 + (((k2 * 4 + quad) ^ (l15 & 7)) << 3));
;       __builtin_amdgcn_sched_barrier(0);
;       __builtin_amdgcn_s_setprio(1);
; #pragma unroll
;       for (int k2 = 0; k2 < 2; ++k2)
; #pragma unroll
;         for (int dt = 0; dt < 4; ++dt)
; #pragma unroll
;           for (int qt = 0; qt < 2; ++qt) oacc[dt][qt] = MFMA16(vf[k2][dt], pf[qt][k2], oacc[dt][qt]);
;       __builtin_amdgcn_s_setprio(0);
;       __builtin_amdgcn_sched_barrier(0);
;     }
;   };
;   ATT_LOAD(rkA, rvA, 0); ATT_LOAD(rkB, rvB, 1);
;   ATT_STORE(rkA, rvA, 0);
;   __syncthreads();
; #pragma unroll 1
;   for (int t = 0; t < NT; t += 2) {
;     if (t + 2 < NT) ATT_LOAD(rkA, rvA, t + 2);
;     compute(sK[0], sV[0], t == 0);
;     ATT_STORE(rkB, rvB, 1);
;     __syncthreads();
;     if (t + 3 < NT) ATT_LOAD(rkB, rvB, t + 3);
.LBB0_380:
	v_exp_f32_e32 v173, v124
	v_exp_f32_e32 v169, v126
	v_exp_f32_e32 v161, v122
	v_exp_f32_e32 v172, v108
	v_exp_f32_e32 v170, v109
	v_exp_f32_e32 v168, v110
	v_exp_f32_e32 v166, v111
	v_exp_f32_e32 v164, v104
	v_exp_f32_e32 v162, v105
	v_exp_f32_e32 v160, v106
	v_exp_f32_e32 v158, v107
	v_exp_f32_e32 v156, v100
	v_exp_f32_e32 v126, v101
	v_exp_f32_e32 v124, v102
	v_exp_f32_e32 v122, v103
	ds_read_b128 v[100:103], v187 offset:16384
	ds_read_b128 v[104:107], v187 offset:18432
	ds_read_b128 v[108:111], v187 offset:20480
	ds_read_b128 v[200:203], v187 offset:22528
	ds_read_b128 v[204:207], v188 offset:16384
	ds_read_b128 v[208:211], v188 offset:18432
	ds_read_b128 v[212:215], v188 offset:20480
	ds_read_b128 v[216:219], v188 offset:22528
	v_exp_f32_e32 v171, v125
	v_exp_f32_e32 v167, v127
	v_exp_f32_e32 v165, v120
	v_exp_f32_e32 v163, v121
	v_exp_f32_e32 v159, v123
	v_exp_f32_e32 v157, v116
	v_exp_f32_e32 v127, v117
	v_exp_f32_e32 v125, v118
	v_exp_f32_e32 v123, v119
	v_exp_f32_e32 v121, v112
	v_exp_f32_e32 v119, v113
	v_exp_f32_e32 v117, v114
	v_exp_f32_e32 v113, v115
	v_exp_f32_e32 v120, v96
	v_exp_f32_e32 v118, v97
	v_exp_f32_e32 v116, v98
	v_exp_f32_e32 v112, v99
	v_cvt_pk_bf16_f32 v192, v173, v171
	v_cvt_pk_bf16_f32 v193, v169, v167
	v_cvt_pk_bf16_f32 v194, v165, v163
	v_cvt_pk_bf16_f32 v195, v161, v159
	v_cvt_pk_bf16_f32 v196, v157, v127
	v_cvt_pk_bf16_f32 v197, v125, v123
	v_cvt_pk_bf16_f32 v198, v121, v119
	v_cvt_pk_bf16_f32 v199, v117, v113
	v_cvt_pk_bf16_f32 v96, v172, v170
	v_cvt_pk_bf16_f32 v97, v168, v166
	v_cvt_pk_bf16_f32 v98, v164, v162
	v_cvt_pk_bf16_f32 v99, v160, v158
	v_cvt_pk_bf16_f32 v220, v156, v126
	v_cvt_pk_bf16_f32 v221, v124, v122
	v_cvt_pk_bf16_f32 v222, v120, v118
	v_cvt_pk_bf16_f32 v223, v116, v112
	s_setprio 1
	s_waitcnt lgkmcnt(7)
	v_mfma_f32_16x16x32_bf16 v[92:95], v[100:103], v[192:195], v[92:95]
	v_mfma_f32_16x16x32_bf16 v[76:79], v[100:103], v[96:99], v[76:79]
	s_waitcnt lgkmcnt(6)
	v_mfma_f32_16x16x32_bf16 v[100:103], v[104:107], v[192:195], v[88:91]
	v_mfma_f32_16x16x32_bf16 v[72:75], v[104:107], v[96:99], v[72:75]
	s_waitcnt lgkmcnt(5)
	v_mfma_f32_16x16x32_bf16 v[104:107], v[108:111], v[192:195], v[84:87]
	v_mfma_f32_16x16x32_bf16 v[68:71], v[108:111], v[96:99], v[68:71]
	s_waitcnt lgkmcnt(4)
	v_mfma_f32_16x16x32_bf16 v[108:111], v[200:203], v[192:195], v[80:83]
	v_mfma_f32_16x16x32_bf16 v[64:67], v[200:203], v[96:99], v[64:67]
	s_waitcnt lgkmcnt(3)
	v_mfma_f32_16x16x32_bf16 v[92:95], v[204:207], v[196:199], v[92:95]
	v_mfma_f32_16x16x32_bf16 v[88:91], v[204:207], v[220:223], v[76:79]
	s_waitcnt lgkmcnt(2)
	v_mfma_f32_16x16x32_bf16 v[84:87], v[208:211], v[196:199], v[100:103]
	v_mfma_f32_16x16x32_bf16 v[80:83], v[208:211], v[220:223], v[72:75]
	s_waitcnt lgkmcnt(1)
	v_mfma_f32_16x16x32_bf16 v[76:79], v[212:215], v[196:199], v[104:107]
	v_mfma_f32_16x16x32_bf16 v[72:75], v[212:215], v[220:223], v[68:71]
	s_waitcnt lgkmcnt(0)
	v_mfma_f32_16x16x32_bf16 v[68:71], v[216:219], v[196:199], v[108:111]
	v_mfma_f32_16x16x32_bf16 v[64:67], v[216:219], v[220:223], v[64:67]
	s_setprio 0
	s_cmp_ge_u32 s3, s2
	s_waitcnt vmcnt(4)
	ds_write_b128 v179, v[44:47] offset:24576
	s_waitcnt vmcnt(3)
	ds_write_b128 v180, v[48:51] offset:24576
	s_waitcnt vmcnt(2)
	ds_write_b128 v181, v[52:55] offset:24576
	s_waitcnt vmcnt(1)
	ds_write_b128 v182, v[56:59] offset:40960
	s_waitcnt vmcnt(0)
	ds_write_b128 v183, v[60:63] offset:40960
	s_waitcnt lgkmcnt(0)
	s_barrier
	s_cbranch_scc1 .LBB0_382
	v_lshl_add_u64 v[44:45], v[142:143], 0, s[98:99]
	v_lshl_add_u64 v[48:49], v[140:141], 0, s[98:99]
	v_lshl_add_u64 v[52:53], v[138:139], 0, s[98:99]
	global_load_dwordx4 v[44:47], v[44:45], off
	s_nop 0
	global_load_dwordx4 v[48:51], v[48:49], off
	s_nop 0
	global_load_dwordx4 v[52:55], v[52:53], off
	global_load_dwordx4 v[56:59], v[134:135], off offset:384
	global_load_dwordx4 v[60:63], v[136:137], off offset:384

; __global__ void __launch_bounds__(256, 2) mega(Params p) {
;   __shared__ __attribute__((aligned(16))) char smem[73728];
;   cg::grid_group grid = cg::this_grid();
	.amdhsa_kernel _Z4mega6Params
		.amdhsa_group_segment_fixed_size 73728
		.amdhsa_private_segment_fixed_size 0
		.amdhsa_kernarg_size 424
		.amdhsa_user_sgpr_count 2
		.amdhsa_user_sgpr_dispatch_ptr 0
		.amdhsa_user_sgpr_queue_ptr 0
		.amdhsa_user_sgpr_kernarg_segment_ptr 1
		.amdhsa_user_sgpr_dispatch_id 0
		.amdhsa_user_sgpr_kernarg_preload_length 0
		.amdhsa_user_sgpr_kernarg_preload_offset 0
		.amdhsa_user_sgpr_private_segment_size 0
		.amdhsa_uses_dynamic_stack 0
		.amdhsa_enable_private_segment 0
		.amdhsa_system_sgpr_workgroup_id_x 1
		.amdhsa_system_sgpr_workgroup_id_y 0
		.amdhsa_system_sgpr_workgroup_id_z 0
		.amdhsa_system_sgpr_workgroup_info 0
		.amdhsa_system_vgpr_workitem_id 2
		.amdhsa_next_free_vgpr 225
		.amdhsa_next_free_sgpr 100
		.amdhsa_accum_offset 228
		.amdhsa_reserve_vcc 1
		.amdhsa_float_round_mode_32 0
		.amdhsa_float_round_mode_16_64 0
		.amdhsa_float_denorm_mode_32 3
		.amdhsa_float_denorm_mode_16_64 3
		.amdhsa_dx10_clamp 1
		.amdhsa_ieee_mode 1
		.amdhsa_fp16_overflow 0
		.amdhsa_tg_split 0
		.amdhsa_exception_fp_ieee_invalid_op 0
		.amdhsa_exception_fp_denorm_src 0
		.amdhsa_exception_fp_ieee_div_zero 0
		.amdhsa_exception_fp_ieee_overflow 0
		.amdhsa_exception_fp_ieee_underflow 0
		.amdhsa_exception_fp_ieee_inexact 0
		.amdhsa_exception_int_div_zero 0
	.end_amdhsa_kernel

; __global__ void __launch_bounds__(256, 2) mega(Params p) {
;   __shared__ __attribute__((aligned(16))) char smem[73728];
;   cg::grid_group grid = cg::this_grid();
amdhsa.kernels:
  - .agpr_count:     0
    .args:
      - .offset:         0
        .size:           168
        .value_kind:     by_value
      - .offset:         168
        .size:           4
        .value_kind:     hidden_block_count_x
      - .offset:         172
        .size:           4
        .value_kind:     hidden_block_count_y
      - .offset:         176
        .size:           4
        .value_kind:     hidden_block_count_z
      - .offset:         180
        .size:           2
        .value_kind:     hidden_group_size_x
      - .offset:         182
        .size:           2
        .value_kind:     hidden_group_size_y
      - .offset:         184
        .size:           2
        .value_kind:     hidden_group_size_z
      - .offset:         186
        .size:           2
        .value_kind:     hidden_remainder_x
      - .offset:         188
        .size:           2
        .value_kind:     hidden_remainder_y
      - .offset:         190
        .size:           2
        .value_kind:     hidden_remainder_z
      - .offset:         208
        .size:           8
        .value_kind:     hidden_global_offset_x
      - .offset:         216
        .size:           8
        .value_kind:     hidden_global_offset_y
      - .offset:         224
        .size:           8
        .value_kind:     hidden_global_offset_z
      - .offset:         232
        .size:           2
        .value_kind:     hidden_grid_dims
      - .offset:         256
        .size:           8
        .value_kind:     hidden_multigrid_sync_arg
    .group_segment_fixed_size: 73728
    .kernarg_segment_align: 8
    .kernarg_segment_size: 424
    .language:       OpenCL C
    .language_version:
      - 2
      - 0
    .max_flat_workgroup_size: 256
    .name:           _Z4mega6Params
    .private_segment_fixed_size: 0
    .sgpr_count:     106
    .sgpr_spill_count: 35
    .symbol:         _Z4mega6Params.kd
    .uniform_work_group_size: 1
    .uses_dynamic_stack: false
    .vgpr_count:     225
    .vgpr_spill_count: 0
    .wavefront_size: 64
